# g1 units: v-tile loads deferred behind the alpha-weight loads (fly during gla_cb); on top of v26 (g3 deferred loads)
# speedup vs baseline: 1.0084x; 1.0084x over previous
.LBB0_418:
	s_or_b64 exec, exec, s[12:13]
	s_waitcnt vmcnt(0)
	v_readlane_b32 s1, v249, 30
	v_and_b32_e32 v21, 15, v43
	v_and_b32_e32 v138, 48, v42
	v_lshl_add_u32 v26, v55, 1, s1
	v_mad_u64_u32 v[18:19], s[12:13], v18, s10, v[26:27]
	ds_write_b16 v18, v0
	ds_write_b16_d16_hi v18, v0 offset:272
	ds_write_b16 v18, v1 offset:544
	ds_write_b16_d16_hi v18, v1 offset:816
	ds_write_b16 v18, v2 offset:1088
	ds_write_b16_d16_hi v18, v2 offset:1360
	ds_write_b16 v18, v3 offset:1632
	ds_write_b16_d16_hi v18, v3 offset:1904
	v_mad_u64_u32 v[0:1], s[12:13], v20, s10, v[26:27]
	ds_write_b16 v0, v8
	ds_write_b16_d16_hi v0, v8 offset:272
	ds_write_b16 v0, v9 offset:544
	ds_write_b16_d16_hi v0, v9 offset:816
	ds_write_b16 v0, v10 offset:1088
	ds_write_b16_d16_hi v0, v10 offset:1360
	ds_write_b16 v0, v11 offset:1632
	ds_write_b16_d16_hi v0, v11 offset:1904
	v_mad_u64_u32 v[0:1], s[12:13], v22, s10, v[26:27]
	ds_write_b16 v0, v4
	ds_write_b16_d16_hi v0, v4 offset:272
	ds_write_b16 v0, v5 offset:544
	ds_write_b16_d16_hi v0, v5 offset:816
	ds_write_b16 v0, v6 offset:1088
	ds_write_b16_d16_hi v0, v6 offset:1360
	ds_write_b16 v0, v7 offset:1632
	ds_write_b16_d16_hi v0, v7 offset:1904
	v_mad_u64_u32 v[0:1], s[12:13], v24, s10, v[26:27]
	ds_write_b16 v0, v12
	ds_write_b16_d16_hi v0, v12 offset:272
	ds_write_b16 v0, v13 offset:544
	ds_write_b16_d16_hi v0, v13 offset:816
	ds_write_b16 v0, v14 offset:1088
	ds_write_b16_d16_hi v0, v14 offset:1360
	ds_write_b16 v0, v15 offset:1632
	ds_write_b16_d16_hi v0, v15 offset:1904
	v_or_b32_e32 v0, v16, v21
	v_mul_u32_u24_e32 v2, 0x110, v21
	v_mul_lo_u32 v0, v0, s10
	v_add3_u32 v26, 0, v138, v2
	s_waitcnt lgkmcnt(0)
	s_barrier
	v_add3_u32 v22, s1, v0, v138
	ds_read_b128 v[2:5], v26 offset:51200
	ds_read_b128 v[6:9], v22
	s_ashr_i32 s1, s0, 31
	s_lshl_b64 s[0:1], s[0:1], 7
	v_lshl_add_u64 v[0:1], s[0:1], 0, v[16:17]
	ds_read_b128 v[10:13], v26 offset:51264
	ds_read_b128 v[14:17], v22 offset:64
	s_waitcnt lgkmcnt(2)
	v_mfma_f32_16x16x32_bf16 v[2:5], v[2:5], v[6:9], 0
	v_or_b32_e32 v0, v0, v21
	v_lshlrev_b64 v[0:1], 8, v[0:1]
	v_lshl_add_u64 v[0:1], s[4:5], 0, v[0:1]
	s_waitcnt lgkmcnt(0)
	v_mfma_f32_16x16x32_bf16 v[2:5], v[10:13], v[14:17], v[2:5]
	ds_read_b128 v[10:13], v26 offset:51328
	ds_read_b128 v[18:21], v22 offset:128
	v_lshl_add_u64 v[0:1], v[0:1], 0, v[138:139]
	s_add_i32 s20, s20, s96
	s_waitcnt lgkmcnt(0)
	v_mfma_f32_16x16x32_bf16 v[2:5], v[10:13], v[18:21], v[2:5]
	ds_read_b128 v[10:13], v26 offset:51392
	ds_read_b128 v[22:25], v22 offset:192
	s_cmpk_gt_i32 s20, 0x1ff
	s_waitcnt lgkmcnt(0)
	v_mfma_f32_16x16x32_bf16 v[2:5], v[10:13], v[22:25], v[2:5]
	ds_read_b128 v[10:13], v26 offset:55616
	s_nop 6
	global_store_dwordx4 v[0:1], v[2:5], off
	ds_read_b128 v[2:5], v26 offset:55552
	s_waitcnt lgkmcnt(0)
	v_mfma_f32_16x16x32_bf16 v[2:5], v[2:5], v[6:9], 0
	v_mfma_f32_16x16x32_bf16 v[2:5], v[10:13], v[14:17], v[2:5]
	ds_read_b128 v[10:13], v26 offset:55680
	s_waitcnt lgkmcnt(0)
	v_mfma_f32_16x16x32_bf16 v[2:5], v[10:13], v[18:21], v[2:5]
	ds_read_b128 v[10:13], v26 offset:55744
	s_waitcnt lgkmcnt(0)
	v_mfma_f32_16x16x32_bf16 v[2:5], v[10:13], v[22:25], v[2:5]
	ds_read_b128 v[10:13], v26 offset:59968
	s_nop 6
	global_store_dwordx4 v[0:1], v[2:5], off offset:64
	ds_read_b128 v[2:5], v26 offset:59904
	s_waitcnt lgkmcnt(0)
	v_mfma_f32_16x16x32_bf16 v[2:5], v[2:5], v[6:9], 0
	v_mfma_f32_16x16x32_bf16 v[2:5], v[10:13], v[14:17], v[2:5]
	ds_read_b128 v[10:13], v26 offset:60032
	s_waitcnt lgkmcnt(0)
	v_mfma_f32_16x16x32_bf16 v[2:5], v[10:13], v[18:21], v[2:5]
	ds_read_b128 v[10:13], v26 offset:60096
	s_waitcnt lgkmcnt(0)
	v_mfma_f32_16x16x32_bf16 v[2:5], v[10:13], v[22:25], v[2:5]
	s_nop 7
	global_store_dwordx4 v[0:1], v[2:5], off offset:128
	ds_read_b128 v[2:5], v26 offset:64256
	s_waitcnt lgkmcnt(0)
	v_mfma_f32_16x16x32_bf16 v[2:5], v[2:5], v[6:9], 0
	ds_read_b128 v[6:9], v26 offset:64320
	s_waitcnt lgkmcnt(0)
	v_mfma_f32_16x16x32_bf16 v[2:5], v[6:9], v[14:17], v[2:5]
	ds_read_b128 v[6:9], v26 offset:64384
	s_waitcnt lgkmcnt(0)
	v_mfma_f32_16x16x32_bf16 v[2:5], v[6:9], v[18:21], v[2:5]
	ds_read_b128 v[6:9], v26 offset:64448
	s_waitcnt lgkmcnt(0)
	v_mfma_f32_16x16x32_bf16 v[2:5], v[6:9], v[22:25], v[2:5]
	s_nop 7
	global_store_dwordx4 v[0:1], v[2:5], off offset:192
	s_barrier
	s_cbranch_scc1 .LBB0_415
.LBB0_419:
	s_ashr_i32 s13, s20, 8
	s_and_b32 s12, s20, 63
	v_mov_b32_e32 v43, v136
	s_bfe_u32 s21, s20, 0x20006
	s_mul_i32 s0, s13, 0x2080
	v_ashrrev_i32_e32 v44, 6, v43
	s_lshl_b32 s26, s12, 7
	s_mul_hi_i32 s1, s13, 0x2080
	s_add_u32 s0, s0, s26
	v_lshlrev_b32_e32 v16, 4, v44
	s_addc_u32 s1, s1, 0
	v_ashrrev_i32_e32 v17, 31, v16
	v_lshl_add_u64 v[0:1], s[0:1], 0, v[16:17]
	v_mov_b64_e32 v[2:3], s[6:7]
	v_mad_u64_u32 v[4:5], s[34:35], v0, s22, v[2:3]
	v_and_b32_e32 v42, 63, v43
	v_mad_i32_i24 v5, v1, s22, v5
	s_lshl_b32 s74, s21, 7
	v_lshl_add_u64 v[0:1], v[4:5], 0, s[74:75]
	v_lshlrev_b32_e32 v138, 1, v42
	v_lshl_add_u64 v[0:1], v[0:1], 0, v[138:139]
	s_movk_i32 s19, 0x3000
	v_add_co_u32_e32 v4, vcc, s19, v0
	s_movk_i32 s18, 0x5000
	s_nop 0
	v_addc_co_u32_e32 v5, vcc, 0, v1, vcc
	global_load_ushort v45, v[0:1], off offset:3584
	global_load_ushort v48, v[4:5], off offset:1536
	v_add_co_u32_e32 v4, vcc, s18, v0
	s_mov_b32 s18, 0x8000
	s_nop 0
	v_addc_co_u32_e32 v5, vcc, 0, v1, vcc
	global_load_ushort v46, v[4:5], off offset:3584
	v_add_co_u32_e32 v4, vcc, s18, v0
	s_mov_b32 s18, 0xa000
	s_nop 0
	v_addc_co_u32_e32 v5, vcc, 0, v1, vcc
	global_load_ushort v50, v[4:5], off offset:1536
	v_add_co_u32_e32 v4, vcc, s18, v0
	s_mov_b32 s18, 0xd000
	s_nop 0
	v_addc_co_u32_e32 v5, vcc, 0, v1, vcc
	global_load_ushort v47, v[4:5], off offset:3584
	v_add_co_u32_e32 v4, vcc, s18, v0
	s_mov_b32 s18, 0xf000
	s_nop 0
	v_addc_co_u32_e32 v5, vcc, 0, v1, vcc
	global_load_ushort v51, v[4:5], off offset:1536
	v_add_co_u32_e32 v4, vcc, s18, v0
	s_mov_b32 s18, 0x12000
	s_nop 0
	v_addc_co_u32_e32 v5, vcc, 0, v1, vcc
	global_load_ushort v49, v[4:5], off offset:3584
	v_add_co_u32_e32 v4, vcc, s18, v0
	s_mov_b32 s18, 0x17000
	s_nop 0
	v_addc_co_u32_e32 v5, vcc, 0, v1, vcc
	global_load_ushort v60, v[4:5], off offset:1536
	v_add_co_u32_e32 v4, vcc, s88, v0
	v_and_b32_e32 v55, 0x7f, v43
	s_nop 0
	v_addc_co_u32_e32 v5, vcc, 0, v1, vcc
	global_load_ushort v52, v[4:5], off offset:3584
	v_add_co_u32_e32 v4, vcc, s18, v0
	s_mov_b32 s18, 0x19000
	s_nop 0
	v_addc_co_u32_e32 v5, vcc, 0, v1, vcc
	global_load_ushort v57, v[4:5], off offset:1536
	v_add_co_u32_e32 v4, vcc, s18, v0
	s_mov_b32 s18, 0x1c000
	s_nop 0
	v_addc_co_u32_e32 v5, vcc, 0, v1, vcc
	global_load_ushort v53, v[4:5], off offset:3584
	v_add_co_u32_e32 v4, vcc, s18, v0
	s_mov_b32 s18, 0x1e000
	s_nop 0
	v_addc_co_u32_e32 v5, vcc, 0, v1, vcc
	global_load_ushort v58, v[4:5], off offset:1536
	v_add_co_u32_e32 v4, vcc, s18, v0
	s_mov_b32 s18, 0x21000
	s_nop 0
	v_addc_co_u32_e32 v5, vcc, 0, v1, vcc
	global_load_ushort v56, v[4:5], off offset:3584
	v_add_co_u32_e32 v4, vcc, s18, v0
	s_mov_b32 s18, 0x23000
	s_nop 0
	v_addc_co_u32_e32 v5, vcc, 0, v1, vcc
	global_load_ushort v59, v[4:5], off offset:1536
	v_add_co_u32_e32 v4, vcc, s18, v0
	s_mov_b32 s18, 0x26000
	s_nop 0
	v_addc_co_u32_e32 v5, vcc, 0, v1, vcc
	v_add_co_u32_e32 v0, vcc, s18, v0
	global_load_ushort v54, v[4:5], off offset:3584
	s_nop 0
	v_addc_co_u32_e32 v1, vcc, 0, v1, vcc
	global_load_ushort v61, v[0:1], off offset:1536
	s_lshl_b32 s27, s21, 6
	v_mov_b32_e32 v23, v136
	s_mov_b64 s[100:101], s[0:1]
	s_lshl_b64 s[0:1], s[0:1], 6
	s_add_u32 s0, s78, s0
	s_addc_u32 s1, s79, s1
	v_lshlrev_b32_e32 v26, 2, v23
	v_ashrrev_i32_e32 v27, 31, v26
	v_lshl_add_u64 v[26:27], v[26:27], 2, s[0:1]
	global_load_dwordx4 v[26:29], v[26:27], off
	v_and_b32_e32 v19, 63, v23
	s_or_b32 s0, s27, s83
	v_readlane_b32 s36, v251, 8
	v_or_b32_e32 v138, s0, v19
	v_readlane_b32 s42, v251, 14
	v_readlane_b32 s43, v251, 15
	v_lshl_add_u32 v21, v23, 4, 0
	v_add_u32_e32 v21, 0x1e000, v21
	v_lshl_add_u64 v[62:63], v[138:139], 2, s[42:43]
	v_add_co_u32_e32 v34, vcc, s97, v62
	s_or_b32 s0, s27, s77
	s_nop 0
	v_addc_co_u32_e32 v35, vcc, 0, v63, vcc
	v_add_co_u32_e32 v38, vcc, s8, v62
	v_readlane_b32 s44, v251, 16
	s_nop 0
	v_addc_co_u32_e32 v39, vcc, 0, v63, vcc
	v_readlane_b32 s45, v251, 17
	v_or_b32_e32 v138, s0, v19
	s_sub_i32 s26, 0x6f, s26
	v_mov_b32_e32 v25, 0
	v_readlane_b32 s37, v251, 9
	v_readlane_b32 s38, v251, 10
	v_readlane_b32 s39, v251, 11
	v_readlane_b32 s40, v251, 12
	v_readlane_b32 s41, v251, 13
	v_readlane_b32 s46, v251, 18
	v_readlane_b32 s47, v251, 19
	v_readlane_b32 s48, v251, 20
	v_readlane_b32 s49, v251, 21
	v_readlane_b32 s50, v251, 22
	v_readlane_b32 s51, v251, 23
	s_waitcnt vmcnt(0)
	ds_write_b128 v21, v[26:29]
	global_load_dword v26, v[62:63], off
	global_load_dword v32, v[62:63], off offset:1024
	global_load_dword v28, v[62:63], off offset:2048
	global_load_dword v30, v[62:63], off offset:3072
	global_load_dword v27, v[38:39], off offset:-4096
	global_load_dword v33, v[34:35], off offset:1024
	global_load_dword v29, v[34:35], off offset:2048
	global_load_dword v31, v[34:35], off offset:3072
	s_nop 0
	global_load_dword v34, v[38:39], off
	global_load_dword v40, v[38:39], off offset:1024
	global_load_dword v36, v[38:39], off offset:2048
	s_nop 0
	global_load_dword v38, v[38:39], off offset:3072
	v_add_co_u32_e32 v62, vcc, s19, v62
	v_ashrrev_i32_e32 v21, 6, v23
	s_nop 0
	v_addc_co_u32_e32 v63, vcc, 0, v63, vcc
	global_load_dword v35, v[62:63], off
	global_load_dword v41, v[62:63], off offset:1024
	global_load_dword v37, v[62:63], off offset:2048
	global_load_dword v39, v[62:63], off offset:3072
	v_lshl_add_u64 v[62:63], v[138:139], 2, s[44:45]
	global_load_dword v62, v[62:63], off
	v_or_b32_e32 v0, s100, v55
	v_mad_u64_u32 v[0:1], s[34:35], v0, s22, v[2:3]
	v_mad_i32_i24 v1, s101, v184, v1
	s_lshl_b32 s74, s21, 8
	v_lshl_add_u64 v[0:1], v[0:1], 0, s[74:75]
	s_mov_b64 s[34:35], 0x1000
	v_add_u32_e32 v4, 0x200, v43
	v_lshl_add_u64 v[12:13], v[0:1], 0, s[34:35]
	v_ashrrev_i32_e32 v0, 4, v43
	v_ashrrev_i32_e32 v4, 4, v4
	v_and_b32_e32 v232, -8, v0
	v_and_b32_e32 v234, -8, v4
	v_ashrrev_i32_e32 v233, 31, v232
	v_ashrrev_i32_e32 v235, 31, v234
	v_lshl_add_u64 v[0:1], v[232:233], 1, v[12:13]
	v_lshl_add_u64 v[4:5], v[234:235], 1, v[12:13]
	global_load_dwordx4 v[0:3], v[0:1], off
	v_add_u32_e32 v14, 0x600, v43
	global_load_dwordx4 v[8:11], v[4:5], off
	v_add_u32_e32 v4, 0x400, v43
	v_ashrrev_i32_e32 v4, 4, v4
	v_ashrrev_i32_e32 v14, 4, v14
	v_and_b32_e32 v236, -8, v4
	v_and_b32_e32 v238, -8, v14
	v_ashrrev_i32_e32 v237, 31, v236
	v_ashrrev_i32_e32 v239, 31, v238
	v_lshl_add_u64 v[4:5], v[236:237], 1, v[12:13]
	v_lshl_add_u64 v[12:13], v[238:239], 1, v[12:13]
	global_load_dwordx4 v[4:7], v[4:5], off
	global_load_dwordx4 v[12:15], v[12:13], off
	v_mov_b32_e32 v18, v232
	v_mov_b32_e32 v20, v234
	v_mov_b32_e32 v22, v236
	v_mov_b32_e32 v24, v238
	v_lshlrev_b32_e32 v64, 4, v21
	v_cmp_lt_i32_e32 vcc, s26, v64
	v_mov_b32_e32 v63, 0
	s_waitcnt lgkmcnt(0)
	s_barrier
	s_and_saveexec_b64 s[0:1], vcc
	s_cbranch_execz .LBB0_421
	v_lshl_add_u32 v25, v21, 10, 0
	v_add_u32_e32 v25, 0x1e000, v25
	ds_read_b128 v[66:69], v25
	ds_read_b128 v[70:73], v25 offset:16
	ds_read_b128 v[74:77], v25 offset:32
	ds_read_b128 v[78:81], v25 offset:48
	s_mov_b32 s18, 0x3d800000
	s_waitcnt lgkmcnt(3)
	v_mov_b32_e32 v82, v69
	s_waitcnt lgkmcnt(2)
	v_mov_b32_e32 v83, v73
	v_mov_b32_e32 v73, v70
	v_mov_b32_e32 v70, v67
	v_mov_b32_e32 v69, v72
	v_mov_b32_e32 v72, v66
	s_waitcnt vmcnt(15)
	v_pk_mul_f32 v[66:67], v[32:33], v[70:71]
	s_nop 0
	v_pk_fma_f32 v[66:67], v[26:27], v[72:73], v[66:67]
	s_waitcnt vmcnt(14)
	v_pk_fma_f32 v[66:67], v[28:29], v[68:69], v[66:67]
	s_waitcnt lgkmcnt(0)
	v_mov_b32_e32 v69, v78
	v_mov_b32_e32 v78, v75
	s_waitcnt vmcnt(13)
	v_pk_fma_f32 v[66:67], v[30:31], v[82:83], v[66:67]
	v_mov_b32_e32 v68, v74
	s_waitcnt vmcnt(7)
	v_pk_mul_f32 v[70:71], v[40:41], v[78:79]
	s_waitcnt vmcnt(4)
	v_add_f32_e32 v25, v62, v66
	v_mov_b32_e32 v66, v77
	v_mov_b32_e32 v77, v80
	v_pk_fma_f32 v[68:69], v[34:35], v[68:69], v[70:71]
	v_add_f32_e32 v25, v25, v67
	v_mov_b32_e32 v67, v81
	v_pk_fma_f32 v[68:69], v[36:37], v[76:77], v[68:69]
	s_nop 0
	v_pk_fma_f32 v[66:67], v[38:39], v[66:67], v[68:69]
	s_nop 0
	v_add_f32_e32 v25, v25, v66
	v_add_f32_e32 v25, v25, v67
	v_mul_f32_e64 v65, |v25|, s31
	v_exp_f32_e32 v65, v65
	v_min_f32_e32 v25, 0, v25
	v_add_f32_e32 v65, 1.0, v65
	v_cmp_gt_f32_e32 vcc, s28, v65
	s_nop 1
	v_cndmask_b32_e64 v66, 0, 32, vcc
	v_ldexp_f32 v65, v65, v66
	v_log_f32_e32 v65, v65
	s_nop 0
	v_mul_f32_e32 v66, 0x3f317217, v65
	v_fma_f32 v66, v65, s29, -v66
	v_fmac_f32_e32 v66, 0x3377d1cf, v65
	v_fmac_f32_e32 v66, 0x3f317217, v65
	v_cmp_lt_f32_e64 s[38:39], |v65|, s30
	s_nop 1
	v_cndmask_b32_e64 v65, v65, v66, s[38:39]
	v_cndmask_b32_e32 v66, 0, v180, vcc
	v_sub_f32_e32 v65, v65, v66
	v_sub_f32_e32 v25, v25, v65
	v_fma_f32 v25, v25, s18, 0
.LBB0_421:
	s_or_b64 exec, exec, s[0:1]
	v_cmp_le_i32_e32 vcc, s26, v64
	s_and_saveexec_b64 s[0:1], vcc
	s_cbranch_execz .LBB0_423
	s_add_i32 s27, 0, 0x1e000
	v_lshl_add_u32 v63, v21, 10, s27
	ds_read_b128 v[66:69], v63 offset:64
	ds_read_b128 v[70:73], v63 offset:80
	ds_read_b128 v[74:77], v63 offset:96
	ds_read_b128 v[78:81], v63 offset:112
	s_waitcnt lgkmcnt(3)
	v_mov_b32_e32 v82, v69
	s_waitcnt lgkmcnt(2)
	v_mov_b32_e32 v83, v73
	v_mov_b32_e32 v73, v70
	v_mov_b32_e32 v70, v67
	v_mov_b32_e32 v69, v72
	v_mov_b32_e32 v72, v66
	s_waitcnt vmcnt(15)
	v_pk_mul_f32 v[66:67], v[32:33], v[70:71]
	s_nop 0
	v_pk_fma_f32 v[66:67], v[26:27], v[72:73], v[66:67]
	s_waitcnt vmcnt(14)
	v_pk_fma_f32 v[66:67], v[28:29], v[68:69], v[66:67]
	s_waitcnt lgkmcnt(0)
	v_mov_b32_e32 v69, v78
	v_mov_b32_e32 v78, v75
	s_waitcnt vmcnt(13)
	v_pk_fma_f32 v[66:67], v[30:31], v[82:83], v[66:67]
	v_mov_b32_e32 v68, v74
	s_waitcnt vmcnt(7)
	v_pk_mul_f32 v[70:71], v[40:41], v[78:79]
	s_waitcnt vmcnt(4)
	v_add_f32_e32 v63, v62, v66
	v_mov_b32_e32 v66, v77
	v_mov_b32_e32 v77, v80
	v_pk_fma_f32 v[68:69], v[34:35], v[68:69], v[70:71]
	v_add_f32_e32 v63, v63, v67
	v_mov_b32_e32 v67, v81
	v_pk_fma_f32 v[68:69], v[36:37], v[76:77], v[68:69]
	s_nop 0
	v_pk_fma_f32 v[66:67], v[38:39], v[66:67], v[68:69]
	s_nop 0
	v_add_f32_e32 v63, v63, v66
	v_add_f32_e32 v63, v63, v67
	v_mul_f32_e64 v65, |v63|, s31
	v_exp_f32_e32 v65, v65
	v_min_f32_e32 v63, 0, v63
	v_add_f32_e32 v65, 1.0, v65
	v_cmp_gt_f32_e32 vcc, s28, v65
	s_nop 1
	v_cndmask_b32_e64 v66, 0, 32, vcc
	v_ldexp_f32 v65, v65, v66
	v_log_f32_e32 v65, v65
	s_nop 0
	v_mul_f32_e32 v66, 0x3f317217, v65
	v_fma_f32 v66, v65, s29, -v66
	v_fmac_f32_e32 v66, 0x3377d1cf, v65
	v_fmac_f32_e32 v66, 0x3f317217, v65
	v_cmp_lt_f32_e64 s[38:39], |v65|, s30
	s_nop 1
	v_cndmask_b32_e64 v65, v65, v66, s[38:39]
	v_cndmask_b32_e32 v66, 0, v180, vcc
	v_sub_f32_e32 v65, v65, v66
	v_sub_f32_e32 v63, v63, v65
	v_mul_f32_e32 v63, 0x3d800000, v63
.LBB0_423:
	s_or_b64 exec, exec, s[0:1]
	v_or_b32_e32 v67, 2, v64
	v_cmp_lt_i32_e32 vcc, s26, v67
	v_mov_b32_e32 v65, 0
	v_mov_b32_e32 v66, 0
	s_and_saveexec_b64 s[0:1], vcc
	v_readlane_b32 s74, v249, 43
	s_cbranch_execz .LBB0_425
	v_lshl_add_u32 v66, v67, 6, 0
	v_add_u32_e32 v78, 0x1e000, v66
	ds_read_b128 v[66:69], v78
	ds_read_b128 v[70:73], v78 offset:16
	ds_read_b128 v[74:77], v78 offset:32
	ds_read_b128 v[78:81], v78 offset:48
	s_waitcnt lgkmcnt(3)
	v_mov_b32_e32 v82, v69
	s_waitcnt lgkmcnt(2)
	v_mov_b32_e32 v83, v73
	v_mov_b32_e32 v73, v70
	v_mov_b32_e32 v70, v67
	v_mov_b32_e32 v69, v72
	v_mov_b32_e32 v72, v66
	s_waitcnt vmcnt(15)
	v_pk_mul_f32 v[66:67], v[32:33], v[70:71]
	s_nop 0
	v_pk_fma_f32 v[66:67], v[26:27], v[72:73], v[66:67]
	s_waitcnt vmcnt(14)
	v_pk_fma_f32 v[66:67], v[28:29], v[68:69], v[66:67]
	s_waitcnt lgkmcnt(0)
	v_mov_b32_e32 v69, v78
	s_waitcnt vmcnt(13)
	v_pk_fma_f32 v[66:67], v[30:31], v[82:83], v[66:67]
	v_mov_b32_e32 v78, v75
	s_waitcnt vmcnt(4)
	v_add_f32_e32 v66, v62, v66
	v_mov_b32_e32 v68, v74
	v_pk_mul_f32 v[70:71], v[40:41], v[78:79]
	v_add_f32_e32 v72, v66, v67
	v_mov_b32_e32 v66, v77
	v_mov_b32_e32 v77, v80
	v_pk_fma_f32 v[68:69], v[34:35], v[68:69], v[70:71]
	v_mov_b32_e32 v67, v81
	v_pk_fma_f32 v[68:69], v[36:37], v[76:77], v[68:69]
	s_nop 0
	v_pk_fma_f32 v[66:67], v[38:39], v[66:67], v[68:69]
	s_nop 0
	v_add_f32_e32 v66, v72, v66
	v_add_f32_e32 v66, v66, v67
	v_mul_f32_e64 v67, |v66|, s31
	v_exp_f32_e32 v67, v67
	v_min_f32_e32 v66, 0, v66
	v_add_f32_e32 v67, 1.0, v67
	v_cmp_gt_f32_e32 vcc, s28, v67
	s_nop 1
	v_cndmask_b32_e64 v68, 0, 32, vcc
	v_ldexp_f32 v67, v67, v68
	v_log_f32_e32 v67, v67
	s_nop 0
	v_mul_f32_e32 v68, 0x3f317217, v67
	v_fma_f32 v68, v67, s29, -v68
	v_fmac_f32_e32 v68, 0x3377d1cf, v67
	v_fmac_f32_e32 v68, 0x3f317217, v67
	v_cmp_lt_f32_e64 s[38:39], |v67|, s30
	s_nop 1
	v_cndmask_b32_e64 v67, v67, v68, s[38:39]
	v_cndmask_b32_e32 v68, 0, v180, vcc
	v_sub_f32_e32 v67, v67, v68
	v_sub_f32_e32 v66, v66, v67
	v_mul_f32_e32 v66, 0x3d800000, v66
.LBB0_425:
	s_or_b64 exec, exec, s[0:1]
	v_or_b32_e32 v67, 3, v64
	v_cmp_lt_i32_e32 vcc, s26, v67
	s_and_saveexec_b64 s[0:1], vcc
	s_cbranch_execz .LBB0_427
	v_lshl_add_u32 v65, v67, 6, 0
	v_add_u32_e32 v65, 0x1e000, v65
	ds_read_b128 v[68:71], v65
	ds_read_b128 v[72:75], v65 offset:16
	ds_read_b128 v[76:79], v65 offset:32
	ds_read_b128 v[80:83], v65 offset:48
	s_waitcnt lgkmcnt(3)
	v_mov_b32_e32 v84, v71
	s_waitcnt lgkmcnt(2)
	v_mov_b32_e32 v85, v75
	v_mov_b32_e32 v75, v72
	v_mov_b32_e32 v72, v69
	v_mov_b32_e32 v71, v74
	v_mov_b32_e32 v74, v68
	s_waitcnt vmcnt(15)
	v_pk_mul_f32 v[68:69], v[32:33], v[72:73]
	s_nop 0
	v_pk_fma_f32 v[68:69], v[26:27], v[74:75], v[68:69]
	s_waitcnt vmcnt(14)
	v_pk_fma_f32 v[68:69], v[28:29], v[70:71], v[68:69]
	s_waitcnt lgkmcnt(0)
	v_mov_b32_e32 v71, v80
	v_mov_b32_e32 v80, v77
	s_waitcnt vmcnt(13)
	v_pk_fma_f32 v[68:69], v[30:31], v[84:85], v[68:69]
	v_mov_b32_e32 v70, v76
	s_waitcnt vmcnt(7)
	v_pk_mul_f32 v[72:73], v[40:41], v[80:81]
	s_waitcnt vmcnt(4)
	v_add_f32_e32 v65, v62, v68
	v_mov_b32_e32 v68, v79
	v_mov_b32_e32 v79, v82
	v_pk_fma_f32 v[70:71], v[34:35], v[70:71], v[72:73]
	v_add_f32_e32 v65, v65, v69
	v_mov_b32_e32 v69, v83
	v_pk_fma_f32 v[70:71], v[36:37], v[78:79], v[70:71]
	s_nop 0
	v_pk_fma_f32 v[68:69], v[38:39], v[68:69], v[70:71]
	s_nop 0
	v_add_f32_e32 v65, v65, v68
	v_add_f32_e32 v65, v65, v69
	v_mul_f32_e64 v67, |v65|, s31
	v_exp_f32_e32 v67, v67
	v_min_f32_e32 v65, 0, v65
	v_add_f32_e32 v67, 1.0, v67
	v_cmp_gt_f32_e32 vcc, s28, v67
	s_nop 1
	v_cndmask_b32_e64 v68, 0, 32, vcc
	v_ldexp_f32 v67, v67, v68
	v_log_f32_e32 v67, v67
	s_nop 0
	v_mul_f32_e32 v68, 0x3f317217, v67
	v_fma_f32 v68, v67, s29, -v68
	v_fmac_f32_e32 v68, 0x3377d1cf, v67
	v_fmac_f32_e32 v68, 0x3f317217, v67
	v_cmp_lt_f32_e64 s[38:39], |v67|, s30
	s_nop 1
	v_cndmask_b32_e64 v67, v67, v68, s[38:39]
	v_cndmask_b32_e32 v68, 0, v180, vcc
	v_sub_f32_e32 v67, v67, v68
	v_sub_f32_e32 v65, v65, v67
	v_mul_f32_e32 v65, 0x3d800000, v65
.LBB0_427:
	s_or_b64 exec, exec, s[0:1]
	v_or_b32_e32 v69, 4, v64
	v_cmp_lt_i32_e32 vcc, s26, v69
	v_mov_b32_e32 v67, 0
	v_mov_b32_e32 v68, 0
	s_and_saveexec_b64 s[0:1], vcc
	s_cbranch_execz .LBB0_429
	v_lshl_add_u32 v68, v69, 6, 0
	v_add_u32_e32 v80, 0x1e000, v68
	ds_read_b128 v[68:71], v80
	ds_read_b128 v[72:75], v80 offset:16
	ds_read_b128 v[76:79], v80 offset:32
	ds_read_b128 v[80:83], v80 offset:48
	s_waitcnt lgkmcnt(3)
	v_mov_b32_e32 v84, v71
	s_waitcnt lgkmcnt(2)
	v_mov_b32_e32 v85, v75
	v_mov_b32_e32 v75, v72
	v_mov_b32_e32 v72, v69
	v_mov_b32_e32 v71, v74
	v_mov_b32_e32 v74, v68
	s_waitcnt vmcnt(15)
	v_pk_mul_f32 v[68:69], v[32:33], v[72:73]
	s_nop 0
	v_pk_fma_f32 v[68:69], v[26:27], v[74:75], v[68:69]
	s_waitcnt vmcnt(14)
	v_pk_fma_f32 v[68:69], v[28:29], v[70:71], v[68:69]
	s_waitcnt lgkmcnt(0)
	v_mov_b32_e32 v71, v80
	s_waitcnt vmcnt(13)
	v_pk_fma_f32 v[68:69], v[30:31], v[84:85], v[68:69]
	v_mov_b32_e32 v80, v77
	s_waitcnt vmcnt(4)
	v_add_f32_e32 v68, v62, v68
	v_mov_b32_e32 v70, v76
	v_pk_mul_f32 v[72:73], v[40:41], v[80:81]
	v_add_f32_e32 v74, v68, v69
	v_mov_b32_e32 v68, v79
	v_mov_b32_e32 v79, v82
	v_pk_fma_f32 v[70:71], v[34:35], v[70:71], v[72:73]
	v_mov_b32_e32 v69, v83
	v_pk_fma_f32 v[70:71], v[36:37], v[78:79], v[70:71]
	s_nop 0
	v_pk_fma_f32 v[68:69], v[38:39], v[68:69], v[70:71]
	s_nop 0
	v_add_f32_e32 v68, v74, v68
	v_add_f32_e32 v68, v68, v69
	v_mul_f32_e64 v69, |v68|, s31
	v_exp_f32_e32 v69, v69
	v_min_f32_e32 v68, 0, v68
	v_add_f32_e32 v69, 1.0, v69
	v_cmp_gt_f32_e32 vcc, s28, v69
	s_nop 1
	v_cndmask_b32_e64 v70, 0, 32, vcc
	v_ldexp_f32 v69, v69, v70
	v_log_f32_e32 v69, v69
	s_nop 0
	v_mul_f32_e32 v70, 0x3f317217, v69
	v_fma_f32 v70, v69, s29, -v70
	v_fmac_f32_e32 v70, 0x3377d1cf, v69
	v_fmac_f32_e32 v70, 0x3f317217, v69
	v_cmp_lt_f32_e64 s[38:39], |v69|, s30
	s_nop 1
	v_cndmask_b32_e64 v69, v69, v70, s[38:39]
	v_cndmask_b32_e32 v70, 0, v180, vcc
	v_sub_f32_e32 v69, v69, v70
	v_sub_f32_e32 v68, v68, v69
	v_mul_f32_e32 v68, 0x3d800000, v68
.LBB0_429:
	s_or_b64 exec, exec, s[0:1]
	v_or_b32_e32 v69, 5, v64
	v_cmp_lt_i32_e32 vcc, s26, v69
	s_and_saveexec_b64 s[0:1], vcc
	s_cbranch_execz .LBB0_431
	v_lshl_add_u32 v67, v69, 6, 0
	v_add_u32_e32 v67, 0x1e000, v67
	ds_read_b128 v[70:73], v67
	ds_read_b128 v[74:77], v67 offset:16
	ds_read_b128 v[78:81], v67 offset:32
	ds_read_b128 v[82:85], v67 offset:48
	s_waitcnt lgkmcnt(3)
	v_mov_b32_e32 v86, v73
	s_waitcnt lgkmcnt(2)
	v_mov_b32_e32 v87, v77
	v_mov_b32_e32 v77, v74
	v_mov_b32_e32 v74, v71
	v_mov_b32_e32 v73, v76
	v_mov_b32_e32 v76, v70
	s_waitcnt vmcnt(15)
	v_pk_mul_f32 v[70:71], v[32:33], v[74:75]
	s_nop 0
	v_pk_fma_f32 v[70:71], v[26:27], v[76:77], v[70:71]
	s_waitcnt vmcnt(14)
	v_pk_fma_f32 v[70:71], v[28:29], v[72:73], v[70:71]
	s_waitcnt lgkmcnt(0)
	v_mov_b32_e32 v73, v82
	v_mov_b32_e32 v82, v79
	s_waitcnt vmcnt(13)
	v_pk_fma_f32 v[70:71], v[30:31], v[86:87], v[70:71]
	v_mov_b32_e32 v72, v78
	s_waitcnt vmcnt(7)
	v_pk_mul_f32 v[74:75], v[40:41], v[82:83]
	s_waitcnt vmcnt(4)
	v_add_f32_e32 v67, v62, v70
	v_mov_b32_e32 v70, v81
	v_mov_b32_e32 v81, v84
	v_pk_fma_f32 v[72:73], v[34:35], v[72:73], v[74:75]
	v_add_f32_e32 v67, v67, v71
	v_mov_b32_e32 v71, v85
	v_pk_fma_f32 v[72:73], v[36:37], v[80:81], v[72:73]
	s_nop 0
	v_pk_fma_f32 v[70:71], v[38:39], v[70:71], v[72:73]
	s_nop 0
	v_add_f32_e32 v67, v67, v70
	v_add_f32_e32 v67, v67, v71
	v_mul_f32_e64 v69, |v67|, s31
	v_exp_f32_e32 v69, v69
	v_min_f32_e32 v67, 0, v67
	v_add_f32_e32 v69, 1.0, v69
	v_cmp_gt_f32_e32 vcc, s28, v69
	s_nop 1
	v_cndmask_b32_e64 v70, 0, 32, vcc
	v_ldexp_f32 v69, v69, v70
	v_log_f32_e32 v69, v69
	s_nop 0
	v_mul_f32_e32 v70, 0x3f317217, v69
	v_fma_f32 v70, v69, s29, -v70
	v_fmac_f32_e32 v70, 0x3377d1cf, v69
	v_fmac_f32_e32 v70, 0x3f317217, v69
	v_cmp_lt_f32_e64 s[38:39], |v69|, s30
	s_nop 1
	v_cndmask_b32_e64 v69, v69, v70, s[38:39]
	v_cndmask_b32_e32 v70, 0, v180, vcc
	v_sub_f32_e32 v69, v69, v70
	v_sub_f32_e32 v67, v67, v69
	v_mul_f32_e32 v67, 0x3d800000, v67
.LBB0_431:
	s_or_b64 exec, exec, s[0:1]
	v_or_b32_e32 v71, 6, v64
	v_cmp_lt_i32_e32 vcc, s26, v71
	v_mov_b32_e32 v69, 0
	v_mov_b32_e32 v70, 0
	s_and_saveexec_b64 s[0:1], vcc
	s_cbranch_execz .LBB0_433
	v_lshl_add_u32 v70, v71, 6, 0
	v_add_u32_e32 v82, 0x1e000, v70
	ds_read_b128 v[70:73], v82
	ds_read_b128 v[74:77], v82 offset:16
	ds_read_b128 v[78:81], v82 offset:32
	ds_read_b128 v[82:85], v82 offset:48
	s_waitcnt lgkmcnt(3)
	v_mov_b32_e32 v86, v73
	s_waitcnt lgkmcnt(2)
	v_mov_b32_e32 v87, v77
	v_mov_b32_e32 v77, v74
	v_mov_b32_e32 v74, v71
	v_mov_b32_e32 v73, v76
	v_mov_b32_e32 v76, v70
	s_waitcnt vmcnt(15)
	v_pk_mul_f32 v[70:71], v[32:33], v[74:75]
	s_nop 0
	v_pk_fma_f32 v[70:71], v[26:27], v[76:77], v[70:71]
	s_waitcnt vmcnt(14)
	v_pk_fma_f32 v[70:71], v[28:29], v[72:73], v[70:71]
	s_waitcnt lgkmcnt(0)
	v_mov_b32_e32 v73, v82
	s_waitcnt vmcnt(13)
	v_pk_fma_f32 v[70:71], v[30:31], v[86:87], v[70:71]
	v_mov_b32_e32 v82, v79
	s_waitcnt vmcnt(4)
	v_add_f32_e32 v70, v62, v70
	v_mov_b32_e32 v72, v78
	v_pk_mul_f32 v[74:75], v[40:41], v[82:83]
	v_add_f32_e32 v76, v70, v71
	v_mov_b32_e32 v70, v81
	v_mov_b32_e32 v81, v84
	v_pk_fma_f32 v[72:73], v[34:35], v[72:73], v[74:75]
	v_mov_b32_e32 v71, v85
	v_pk_fma_f32 v[72:73], v[36:37], v[80:81], v[72:73]
	s_nop 0
	v_pk_fma_f32 v[70:71], v[38:39], v[70:71], v[72:73]
	s_nop 0
	v_add_f32_e32 v70, v76, v70
	v_add_f32_e32 v70, v70, v71
	v_mul_f32_e64 v71, |v70|, s31
	v_exp_f32_e32 v71, v71
	v_min_f32_e32 v70, 0, v70
	v_add_f32_e32 v71, 1.0, v71
	v_cmp_gt_f32_e32 vcc, s28, v71
	s_nop 1
	v_cndmask_b32_e64 v72, 0, 32, vcc
	v_ldexp_f32 v71, v71, v72
	v_log_f32_e32 v71, v71
	s_nop 0
	v_mul_f32_e32 v72, 0x3f317217, v71
	v_fma_f32 v72, v71, s29, -v72
	v_fmac_f32_e32 v72, 0x3377d1cf, v71
	v_fmac_f32_e32 v72, 0x3f317217, v71
	v_cmp_lt_f32_e64 s[38:39], |v71|, s30
	s_nop 1
	v_cndmask_b32_e64 v71, v71, v72, s[38:39]
	v_cndmask_b32_e32 v72, 0, v180, vcc
	v_sub_f32_e32 v71, v71, v72
	v_sub_f32_e32 v70, v70, v71
	v_mul_f32_e32 v70, 0x3d800000, v70
.LBB0_433:
	s_or_b64 exec, exec, s[0:1]
	v_or_b32_e32 v71, 7, v64
	v_cmp_lt_i32_e32 vcc, s26, v71
	s_and_saveexec_b64 s[0:1], vcc
	s_cbranch_execz .LBB0_435
	v_lshl_add_u32 v69, v71, 6, 0
	v_add_u32_e32 v69, 0x1e000, v69
	ds_read_b128 v[72:75], v69
	ds_read_b128 v[76:79], v69 offset:16
	ds_read_b128 v[80:83], v69 offset:32
	ds_read_b128 v[84:87], v69 offset:48
	s_waitcnt lgkmcnt(3)
	v_mov_b32_e32 v88, v75
	s_waitcnt lgkmcnt(2)
	v_mov_b32_e32 v89, v79
	v_mov_b32_e32 v79, v76
	v_mov_b32_e32 v76, v73
	v_mov_b32_e32 v75, v78
	v_mov_b32_e32 v78, v72
	s_waitcnt vmcnt(15)
	v_pk_mul_f32 v[72:73], v[32:33], v[76:77]
	s_nop 0
	v_pk_fma_f32 v[72:73], v[26:27], v[78:79], v[72:73]
	s_waitcnt vmcnt(14)
	v_pk_fma_f32 v[72:73], v[28:29], v[74:75], v[72:73]
	s_waitcnt lgkmcnt(0)
	v_mov_b32_e32 v75, v84
	v_mov_b32_e32 v84, v81
	s_waitcnt vmcnt(13)
	v_pk_fma_f32 v[72:73], v[30:31], v[88:89], v[72:73]
	v_mov_b32_e32 v74, v80
	s_waitcnt vmcnt(7)
	v_pk_mul_f32 v[76:77], v[40:41], v[84:85]
	s_waitcnt vmcnt(4)
	v_add_f32_e32 v69, v62, v72
	v_mov_b32_e32 v72, v83
	v_mov_b32_e32 v83, v86
	v_pk_fma_f32 v[74:75], v[34:35], v[74:75], v[76:77]
	v_add_f32_e32 v69, v69, v73
	v_mov_b32_e32 v73, v87
	v_pk_fma_f32 v[74:75], v[36:37], v[82:83], v[74:75]
	s_nop 0
	v_pk_fma_f32 v[72:73], v[38:39], v[72:73], v[74:75]
	s_nop 0
	v_add_f32_e32 v69, v69, v72
	v_add_f32_e32 v69, v69, v73
	v_mul_f32_e64 v71, |v69|, s31
	v_exp_f32_e32 v71, v71
	v_min_f32_e32 v69, 0, v69
	v_add_f32_e32 v71, 1.0, v71
	v_cmp_gt_f32_e32 vcc, s28, v71
	s_nop 1
	v_cndmask_b32_e64 v72, 0, 32, vcc
	v_ldexp_f32 v71, v71, v72
	v_log_f32_e32 v71, v71
	s_nop 0
	v_mul_f32_e32 v72, 0x3f317217, v71
	v_fma_f32 v72, v71, s29, -v72
	v_fmac_f32_e32 v72, 0x3377d1cf, v71
	v_fmac_f32_e32 v72, 0x3f317217, v71
	v_cmp_lt_f32_e64 s[38:39], |v71|, s30
	s_nop 1
	v_cndmask_b32_e64 v71, v71, v72, s[38:39]
	v_cndmask_b32_e32 v72, 0, v180, vcc
	v_sub_f32_e32 v71, v71, v72
	v_sub_f32_e32 v69, v69, v71
	v_mul_f32_e32 v69, 0x3d800000, v69
.LBB0_435:
	s_or_b64 exec, exec, s[0:1]
	v_or_b32_e32 v73, 8, v64
	v_cmp_lt_i32_e32 vcc, s26, v73
	v_mov_b32_e32 v71, 0
	v_mov_b32_e32 v72, 0
	s_and_saveexec_b64 s[0:1], vcc
	s_cbranch_execz .LBB0_437
	v_lshl_add_u32 v72, v73, 6, 0
	v_add_u32_e32 v84, 0x1e000, v72
	ds_read_b128 v[72:75], v84
	ds_read_b128 v[76:79], v84 offset:16
	ds_read_b128 v[80:83], v84 offset:32
	ds_read_b128 v[84:87], v84 offset:48
	s_waitcnt lgkmcnt(3)
	v_mov_b32_e32 v88, v75
	s_waitcnt lgkmcnt(2)
	v_mov_b32_e32 v89, v79
	v_mov_b32_e32 v79, v76
	v_mov_b32_e32 v76, v73
	v_mov_b32_e32 v75, v78
	v_mov_b32_e32 v78, v72
	s_waitcnt vmcnt(15)
	v_pk_mul_f32 v[72:73], v[32:33], v[76:77]
	s_nop 0
	v_pk_fma_f32 v[72:73], v[26:27], v[78:79], v[72:73]
	s_waitcnt vmcnt(14)
	v_pk_fma_f32 v[72:73], v[28:29], v[74:75], v[72:73]
	s_waitcnt lgkmcnt(0)
	v_mov_b32_e32 v75, v84
	s_waitcnt vmcnt(13)
	v_pk_fma_f32 v[72:73], v[30:31], v[88:89], v[72:73]
	v_mov_b32_e32 v84, v81
	s_waitcnt vmcnt(4)
	v_add_f32_e32 v72, v62, v72
	v_mov_b32_e32 v74, v80
	v_pk_mul_f32 v[76:77], v[40:41], v[84:85]
	v_add_f32_e32 v78, v72, v73
	v_mov_b32_e32 v72, v83
	v_mov_b32_e32 v83, v86
	v_pk_fma_f32 v[74:75], v[34:35], v[74:75], v[76:77]
	v_mov_b32_e32 v73, v87
	v_pk_fma_f32 v[74:75], v[36:37], v[82:83], v[74:75]
	s_nop 0
	v_pk_fma_f32 v[72:73], v[38:39], v[72:73], v[74:75]
	s_nop 0
	v_add_f32_e32 v72, v78, v72
	v_add_f32_e32 v72, v72, v73
	v_mul_f32_e64 v73, |v72|, s31
	v_exp_f32_e32 v73, v73
	v_min_f32_e32 v72, 0, v72
	v_add_f32_e32 v73, 1.0, v73
	v_cmp_gt_f32_e32 vcc, s28, v73
	s_nop 1
	v_cndmask_b32_e64 v74, 0, 32, vcc
	v_ldexp_f32 v73, v73, v74
	v_log_f32_e32 v73, v73
	s_nop 0
	v_mul_f32_e32 v74, 0x3f317217, v73
	v_fma_f32 v74, v73, s29, -v74
	v_fmac_f32_e32 v74, 0x3377d1cf, v73
	v_fmac_f32_e32 v74, 0x3f317217, v73
	v_cmp_lt_f32_e64 s[38:39], |v73|, s30
	s_nop 1
	v_cndmask_b32_e64 v73, v73, v74, s[38:39]
	v_cndmask_b32_e32 v74, 0, v180, vcc
	v_sub_f32_e32 v73, v73, v74
	v_sub_f32_e32 v72, v72, v73
	v_mul_f32_e32 v72, 0x3d800000, v72
.LBB0_437:
	s_or_b64 exec, exec, s[0:1]
	v_or_b32_e32 v73, 9, v64
	v_cmp_lt_i32_e32 vcc, s26, v73
	s_and_saveexec_b64 s[0:1], vcc
	s_cbranch_execz .LBB0_439
	v_lshl_add_u32 v71, v73, 6, 0
	v_add_u32_e32 v71, 0x1e000, v71
	ds_read_b128 v[74:77], v71
	ds_read_b128 v[78:81], v71 offset:16
	ds_read_b128 v[82:85], v71 offset:32
	ds_read_b128 v[86:89], v71 offset:48
	s_waitcnt lgkmcnt(3)
	v_mov_b32_e32 v90, v77
	s_waitcnt lgkmcnt(2)
	v_mov_b32_e32 v91, v81
	v_mov_b32_e32 v81, v78
	v_mov_b32_e32 v78, v75
	v_mov_b32_e32 v77, v80
	v_mov_b32_e32 v80, v74
	s_waitcnt vmcnt(15)
	v_pk_mul_f32 v[74:75], v[32:33], v[78:79]
	s_nop 0
	v_pk_fma_f32 v[74:75], v[26:27], v[80:81], v[74:75]
	s_waitcnt vmcnt(14)
	v_pk_fma_f32 v[74:75], v[28:29], v[76:77], v[74:75]
	s_waitcnt lgkmcnt(0)
	v_mov_b32_e32 v77, v86
	v_mov_b32_e32 v86, v83
	s_waitcnt vmcnt(13)
	v_pk_fma_f32 v[74:75], v[30:31], v[90:91], v[74:75]
	v_mov_b32_e32 v76, v82
	s_waitcnt vmcnt(7)
	v_pk_mul_f32 v[78:79], v[40:41], v[86:87]
	s_waitcnt vmcnt(4)
	v_add_f32_e32 v71, v62, v74
	v_mov_b32_e32 v74, v85
	v_mov_b32_e32 v85, v88
	v_pk_fma_f32 v[76:77], v[34:35], v[76:77], v[78:79]
	v_add_f32_e32 v71, v71, v75
	v_mov_b32_e32 v75, v89
	v_pk_fma_f32 v[76:77], v[36:37], v[84:85], v[76:77]
	s_nop 0
	v_pk_fma_f32 v[74:75], v[38:39], v[74:75], v[76:77]
	s_nop 0
	v_add_f32_e32 v71, v71, v74
	v_add_f32_e32 v71, v71, v75
	v_mul_f32_e64 v73, |v71|, s31
	v_exp_f32_e32 v73, v73
	v_min_f32_e32 v71, 0, v71
	v_add_f32_e32 v73, 1.0, v73
	v_cmp_gt_f32_e32 vcc, s28, v73
	s_nop 1
	v_cndmask_b32_e64 v74, 0, 32, vcc
	v_ldexp_f32 v73, v73, v74
	v_log_f32_e32 v73, v73
	s_nop 0
	v_mul_f32_e32 v74, 0x3f317217, v73
	v_fma_f32 v74, v73, s29, -v74
	v_fmac_f32_e32 v74, 0x3377d1cf, v73
	v_fmac_f32_e32 v74, 0x3f317217, v73
	v_cmp_lt_f32_e64 s[38:39], |v73|, s30
	s_nop 1
	v_cndmask_b32_e64 v73, v73, v74, s[38:39]
	v_cndmask_b32_e32 v74, 0, v180, vcc
	v_sub_f32_e32 v73, v73, v74
	v_sub_f32_e32 v71, v71, v73
	v_mul_f32_e32 v71, 0x3d800000, v71
.LBB0_439:
	s_or_b64 exec, exec, s[0:1]
	v_or_b32_e32 v75, 10, v64
	v_cmp_lt_i32_e32 vcc, s26, v75
	v_mov_b32_e32 v73, 0
	v_mov_b32_e32 v74, 0
	s_and_saveexec_b64 s[0:1], vcc
	s_cbranch_execz .LBB0_441
	v_lshl_add_u32 v74, v75, 6, 0
	v_add_u32_e32 v86, 0x1e000, v74
	ds_read_b128 v[74:77], v86
	ds_read_b128 v[78:81], v86 offset:16
	ds_read_b128 v[82:85], v86 offset:32
	ds_read_b128 v[86:89], v86 offset:48
	s_waitcnt lgkmcnt(3)
	v_mov_b32_e32 v90, v77
	s_waitcnt lgkmcnt(2)
	v_mov_b32_e32 v91, v81
	v_mov_b32_e32 v81, v78
	v_mov_b32_e32 v78, v75
	v_mov_b32_e32 v77, v80
	v_mov_b32_e32 v80, v74
	s_waitcnt vmcnt(15)
	v_pk_mul_f32 v[74:75], v[32:33], v[78:79]
	s_nop 0
	v_pk_fma_f32 v[74:75], v[26:27], v[80:81], v[74:75]
	s_waitcnt vmcnt(14)
	v_pk_fma_f32 v[74:75], v[28:29], v[76:77], v[74:75]
	s_waitcnt lgkmcnt(0)
	v_mov_b32_e32 v77, v86
	s_waitcnt vmcnt(13)
	v_pk_fma_f32 v[74:75], v[30:31], v[90:91], v[74:75]
	v_mov_b32_e32 v86, v83
	s_waitcnt vmcnt(4)
	v_add_f32_e32 v74, v62, v74
	v_mov_b32_e32 v76, v82
	v_pk_mul_f32 v[78:79], v[40:41], v[86:87]
	v_add_f32_e32 v80, v74, v75
	v_mov_b32_e32 v74, v85
	v_mov_b32_e32 v85, v88
	v_pk_fma_f32 v[76:77], v[34:35], v[76:77], v[78:79]
	v_mov_b32_e32 v75, v89
	v_pk_fma_f32 v[76:77], v[36:37], v[84:85], v[76:77]
	s_nop 0
	v_pk_fma_f32 v[74:75], v[38:39], v[74:75], v[76:77]
	s_nop 0
	v_add_f32_e32 v74, v80, v74
	v_add_f32_e32 v74, v74, v75
	v_mul_f32_e64 v75, |v74|, s31
	v_exp_f32_e32 v75, v75
	v_min_f32_e32 v74, 0, v74
	v_add_f32_e32 v75, 1.0, v75
	v_cmp_gt_f32_e32 vcc, s28, v75
	s_nop 1
	v_cndmask_b32_e64 v76, 0, 32, vcc
	v_ldexp_f32 v75, v75, v76
	v_log_f32_e32 v75, v75
	s_nop 0
	v_mul_f32_e32 v76, 0x3f317217, v75
	v_fma_f32 v76, v75, s29, -v76
	v_fmac_f32_e32 v76, 0x3377d1cf, v75
	v_fmac_f32_e32 v76, 0x3f317217, v75
	v_cmp_lt_f32_e64 s[38:39], |v75|, s30
	s_nop 1
	v_cndmask_b32_e64 v75, v75, v76, s[38:39]
	v_cndmask_b32_e32 v76, 0, v180, vcc
	v_sub_f32_e32 v75, v75, v76
	v_sub_f32_e32 v74, v74, v75
	v_mul_f32_e32 v74, 0x3d800000, v74
.LBB0_441:
	s_or_b64 exec, exec, s[0:1]
	v_or_b32_e32 v75, 11, v64
	v_cmp_lt_i32_e32 vcc, s26, v75
	s_and_saveexec_b64 s[0:1], vcc
	s_cbranch_execz .LBB0_443
	v_lshl_add_u32 v73, v75, 6, 0
	v_add_u32_e32 v73, 0x1e000, v73
	ds_read_b128 v[76:79], v73
	ds_read_b128 v[80:83], v73 offset:16
	ds_read_b128 v[84:87], v73 offset:32
	ds_read_b128 v[88:91], v73 offset:48
	s_waitcnt lgkmcnt(3)
	v_mov_b32_e32 v92, v79
	s_waitcnt lgkmcnt(2)
	v_mov_b32_e32 v93, v83
	v_mov_b32_e32 v83, v80
	v_mov_b32_e32 v80, v77
	v_mov_b32_e32 v79, v82
	v_mov_b32_e32 v82, v76
	s_waitcnt vmcnt(15)
	v_pk_mul_f32 v[76:77], v[32:33], v[80:81]
	s_nop 0
	v_pk_fma_f32 v[76:77], v[26:27], v[82:83], v[76:77]
	s_waitcnt vmcnt(14)
	v_pk_fma_f32 v[76:77], v[28:29], v[78:79], v[76:77]
	s_waitcnt lgkmcnt(0)
	v_mov_b32_e32 v79, v88
	v_mov_b32_e32 v88, v85
	s_waitcnt vmcnt(13)
	v_pk_fma_f32 v[76:77], v[30:31], v[92:93], v[76:77]
	v_mov_b32_e32 v78, v84
	s_waitcnt vmcnt(7)
	v_pk_mul_f32 v[80:81], v[40:41], v[88:89]
	s_waitcnt vmcnt(4)
	v_add_f32_e32 v73, v62, v76
	v_mov_b32_e32 v76, v87
	v_mov_b32_e32 v87, v90
	v_pk_fma_f32 v[78:79], v[34:35], v[78:79], v[80:81]
	v_add_f32_e32 v73, v73, v77
	v_mov_b32_e32 v77, v91
	v_pk_fma_f32 v[78:79], v[36:37], v[86:87], v[78:79]
	s_nop 0
	v_pk_fma_f32 v[76:77], v[38:39], v[76:77], v[78:79]
	s_nop 0
	v_add_f32_e32 v73, v73, v76
	v_add_f32_e32 v73, v73, v77
	v_mul_f32_e64 v75, |v73|, s31
	v_exp_f32_e32 v75, v75
	v_min_f32_e32 v73, 0, v73
	v_add_f32_e32 v75, 1.0, v75
	v_cmp_gt_f32_e32 vcc, s28, v75
	s_nop 1
	v_cndmask_b32_e64 v76, 0, 32, vcc
	v_ldexp_f32 v75, v75, v76
	v_log_f32_e32 v75, v75
	s_nop 0
	v_mul_f32_e32 v76, 0x3f317217, v75
	v_fma_f32 v76, v75, s29, -v76
	v_fmac_f32_e32 v76, 0x3377d1cf, v75
	v_fmac_f32_e32 v76, 0x3f317217, v75
	v_cmp_lt_f32_e64 s[38:39], |v75|, s30
	s_nop 1
	v_cndmask_b32_e64 v75, v75, v76, s[38:39]
	v_cndmask_b32_e32 v76, 0, v180, vcc
	v_sub_f32_e32 v75, v75, v76
	v_sub_f32_e32 v73, v73, v75
	v_mul_f32_e32 v73, 0x3d800000, v73
.LBB0_443:
	s_or_b64 exec, exec, s[0:1]
	v_or_b32_e32 v77, 12, v64
	v_cmp_lt_i32_e32 vcc, s26, v77
	v_mov_b32_e32 v75, 0
	v_mov_b32_e32 v76, 0
	s_and_saveexec_b64 s[0:1], vcc
	s_cbranch_execz .LBB0_445
	v_lshl_add_u32 v76, v77, 6, 0
	v_add_u32_e32 v88, 0x1e000, v76
	ds_read_b128 v[76:79], v88
	ds_read_b128 v[80:83], v88 offset:16
	ds_read_b128 v[84:87], v88 offset:32
	ds_read_b128 v[88:91], v88 offset:48
	s_waitcnt lgkmcnt(3)
	v_mov_b32_e32 v92, v79
	s_waitcnt lgkmcnt(2)
	v_mov_b32_e32 v93, v83
	v_mov_b32_e32 v83, v80
	v_mov_b32_e32 v80, v77
	v_mov_b32_e32 v79, v82
	v_mov_b32_e32 v82, v76
	s_waitcnt vmcnt(15)
	v_pk_mul_f32 v[76:77], v[32:33], v[80:81]
	s_nop 0
	v_pk_fma_f32 v[76:77], v[26:27], v[82:83], v[76:77]
	s_waitcnt vmcnt(14)
	v_pk_fma_f32 v[76:77], v[28:29], v[78:79], v[76:77]
	s_waitcnt lgkmcnt(0)
	v_mov_b32_e32 v79, v88
	s_waitcnt vmcnt(13)
	v_pk_fma_f32 v[76:77], v[30:31], v[92:93], v[76:77]
	v_mov_b32_e32 v88, v85
	s_waitcnt vmcnt(4)
	v_add_f32_e32 v76, v62, v76
	v_mov_b32_e32 v78, v84
	v_pk_mul_f32 v[80:81], v[40:41], v[88:89]
	v_add_f32_e32 v82, v76, v77
	v_mov_b32_e32 v76, v87
	v_mov_b32_e32 v87, v90
	v_pk_fma_f32 v[78:79], v[34:35], v[78:79], v[80:81]
	v_mov_b32_e32 v77, v91
	v_pk_fma_f32 v[78:79], v[36:37], v[86:87], v[78:79]
	s_nop 0
	v_pk_fma_f32 v[76:77], v[38:39], v[76:77], v[78:79]
	s_nop 0
	v_add_f32_e32 v76, v82, v76
	v_add_f32_e32 v76, v76, v77
	v_mul_f32_e64 v77, |v76|, s31
	v_exp_f32_e32 v77, v77
	v_min_f32_e32 v76, 0, v76
	v_add_f32_e32 v77, 1.0, v77
	v_cmp_gt_f32_e32 vcc, s28, v77
	s_nop 1
	v_cndmask_b32_e64 v78, 0, 32, vcc
	v_ldexp_f32 v77, v77, v78
	v_log_f32_e32 v77, v77
	s_nop 0
	v_mul_f32_e32 v78, 0x3f317217, v77
	v_fma_f32 v78, v77, s29, -v78
	v_fmac_f32_e32 v78, 0x3377d1cf, v77
	v_fmac_f32_e32 v78, 0x3f317217, v77
	v_cmp_lt_f32_e64 s[38:39], |v77|, s30
	s_nop 1
	v_cndmask_b32_e64 v77, v77, v78, s[38:39]
	v_cndmask_b32_e32 v78, 0, v180, vcc
	v_sub_f32_e32 v77, v77, v78
	v_sub_f32_e32 v76, v76, v77
	v_mul_f32_e32 v76, 0x3d800000, v76
.LBB0_445:
	s_or_b64 exec, exec, s[0:1]
	v_or_b32_e32 v77, 13, v64
	v_cmp_lt_i32_e32 vcc, s26, v77
	s_and_saveexec_b64 s[0:1], vcc
	s_cbranch_execz .LBB0_447
	v_lshl_add_u32 v75, v77, 6, 0
	v_add_u32_e32 v75, 0x1e000, v75
	ds_read_b128 v[78:81], v75
	ds_read_b128 v[82:85], v75 offset:16
	ds_read_b128 v[86:89], v75 offset:32
	ds_read_b128 v[90:93], v75 offset:48
	s_waitcnt lgkmcnt(3)
	v_mov_b32_e32 v94, v81
	s_waitcnt lgkmcnt(2)
	v_mov_b32_e32 v95, v85
	v_mov_b32_e32 v85, v82
	v_mov_b32_e32 v82, v79
	v_mov_b32_e32 v81, v84
	v_mov_b32_e32 v84, v78
	s_waitcnt vmcnt(15)
	v_pk_mul_f32 v[78:79], v[32:33], v[82:83]
	s_nop 0
	v_pk_fma_f32 v[78:79], v[26:27], v[84:85], v[78:79]
	s_waitcnt vmcnt(14)
	v_pk_fma_f32 v[78:79], v[28:29], v[80:81], v[78:79]
	s_waitcnt lgkmcnt(0)
	v_mov_b32_e32 v81, v90
	v_mov_b32_e32 v90, v87
	s_waitcnt vmcnt(13)
	v_pk_fma_f32 v[78:79], v[30:31], v[94:95], v[78:79]
	v_mov_b32_e32 v80, v86
	s_waitcnt vmcnt(7)
	v_pk_mul_f32 v[82:83], v[40:41], v[90:91]
	s_waitcnt vmcnt(4)
	v_add_f32_e32 v75, v62, v78
	v_mov_b32_e32 v78, v89
	v_mov_b32_e32 v89, v92
	v_pk_fma_f32 v[80:81], v[34:35], v[80:81], v[82:83]
	v_add_f32_e32 v75, v75, v79
	v_mov_b32_e32 v79, v93
	v_pk_fma_f32 v[80:81], v[36:37], v[88:89], v[80:81]
	s_nop 0
	v_pk_fma_f32 v[78:79], v[38:39], v[78:79], v[80:81]
	s_nop 0
	v_add_f32_e32 v75, v75, v78
	v_add_f32_e32 v75, v75, v79
	v_mul_f32_e64 v77, |v75|, s31
	v_exp_f32_e32 v77, v77
	v_min_f32_e32 v75, 0, v75
	v_add_f32_e32 v77, 1.0, v77
	v_cmp_gt_f32_e32 vcc, s28, v77
	s_nop 1
	v_cndmask_b32_e64 v78, 0, 32, vcc
	v_ldexp_f32 v77, v77, v78
	v_log_f32_e32 v77, v77
	s_nop 0
	v_mul_f32_e32 v78, 0x3f317217, v77
	v_fma_f32 v78, v77, s29, -v78
	v_fmac_f32_e32 v78, 0x3377d1cf, v77
	v_fmac_f32_e32 v78, 0x3f317217, v77
	v_cmp_lt_f32_e64 s[38:39], |v77|, s30
	s_nop 1
	v_cndmask_b32_e64 v77, v77, v78, s[38:39]
	v_cndmask_b32_e32 v78, 0, v180, vcc
	v_sub_f32_e32 v77, v77, v78
	v_sub_f32_e32 v75, v75, v77
	v_mul_f32_e32 v75, 0x3d800000, v75
.LBB0_447:
	s_or_b64 exec, exec, s[0:1]
	v_or_b32_e32 v79, 14, v64
	v_cmp_lt_i32_e32 vcc, s26, v79
	v_mov_b32_e32 v77, 0
	v_mov_b32_e32 v78, 0
	s_and_saveexec_b64 s[0:1], vcc
	s_cbranch_execz .LBB0_449
	v_lshl_add_u32 v78, v79, 6, 0
	v_add_u32_e32 v90, 0x1e000, v78
	ds_read_b128 v[78:81], v90
	ds_read_b128 v[82:85], v90 offset:16
	ds_read_b128 v[86:89], v90 offset:32
	ds_read_b128 v[90:93], v90 offset:48
	s_waitcnt lgkmcnt(3)
	v_mov_b32_e32 v94, v81
	s_waitcnt lgkmcnt(2)
	v_mov_b32_e32 v95, v85
	v_mov_b32_e32 v85, v82
	v_mov_b32_e32 v82, v79
	v_mov_b32_e32 v81, v84
	v_mov_b32_e32 v84, v78
	s_waitcnt vmcnt(15)
	v_pk_mul_f32 v[78:79], v[32:33], v[82:83]
	s_nop 0
	v_pk_fma_f32 v[78:79], v[26:27], v[84:85], v[78:79]
	s_waitcnt vmcnt(14)
	v_pk_fma_f32 v[78:79], v[28:29], v[80:81], v[78:79]
	s_waitcnt lgkmcnt(0)
	v_mov_b32_e32 v81, v90
	s_waitcnt vmcnt(13)
	v_pk_fma_f32 v[78:79], v[30:31], v[94:95], v[78:79]
	v_mov_b32_e32 v90, v87
	s_waitcnt vmcnt(4)
	v_add_f32_e32 v78, v62, v78
	v_mov_b32_e32 v80, v86
	v_pk_mul_f32 v[82:83], v[40:41], v[90:91]
	v_add_f32_e32 v84, v78, v79
	v_mov_b32_e32 v78, v89
	v_mov_b32_e32 v89, v92
	v_pk_fma_f32 v[80:81], v[34:35], v[80:81], v[82:83]
	v_mov_b32_e32 v79, v93
	v_pk_fma_f32 v[80:81], v[36:37], v[88:89], v[80:81]
	s_nop 0
	v_pk_fma_f32 v[78:79], v[38:39], v[78:79], v[80:81]
	s_nop 0
	v_add_f32_e32 v78, v84, v78
	v_add_f32_e32 v78, v78, v79
	v_mul_f32_e64 v79, |v78|, s31
	v_exp_f32_e32 v79, v79
	v_min_f32_e32 v78, 0, v78
	v_add_f32_e32 v79, 1.0, v79
	v_cmp_gt_f32_e32 vcc, s28, v79
	s_nop 1
	v_cndmask_b32_e64 v80, 0, 32, vcc
	v_ldexp_f32 v79, v79, v80
	v_log_f32_e32 v79, v79
	s_nop 0
	v_mul_f32_e32 v80, 0x3f317217, v79
	v_fma_f32 v80, v79, s29, -v80
	v_fmac_f32_e32 v80, 0x3377d1cf, v79
	v_fmac_f32_e32 v80, 0x3f317217, v79
	v_cmp_lt_f32_e64 s[38:39], |v79|, s30
	s_nop 1
	v_cndmask_b32_e64 v79, v79, v80, s[38:39]
	v_cndmask_b32_e32 v80, 0, v180, vcc
	v_sub_f32_e32 v79, v79, v80
	v_sub_f32_e32 v78, v78, v79
	v_mul_f32_e32 v78, 0x3d800000, v78
.LBB0_449:
	s_or_b64 exec, exec, s[0:1]
	v_or_b32_e32 v64, 15, v64
	v_cmp_lt_i32_e32 vcc, s26, v64
	s_and_saveexec_b64 s[0:1], vcc
	s_cbranch_execz .LBB0_451
	v_lshl_add_u32 v64, v64, 6, 0
	v_add_u32_e32 v64, 0x1e000, v64
	ds_read_b128 v[80:83], v64
	ds_read_b128 v[84:87], v64 offset:16
	ds_read_b128 v[88:91], v64 offset:32
	ds_read_b128 v[92:95], v64 offset:48
	s_waitcnt lgkmcnt(3)
	v_mov_b32_e32 v96, v83
	s_waitcnt lgkmcnt(2)
	v_mov_b32_e32 v97, v87
	v_mov_b32_e32 v87, v84
	v_mov_b32_e32 v84, v81
	v_mov_b32_e32 v83, v86
	v_mov_b32_e32 v86, v80
	s_waitcnt vmcnt(15)
	v_pk_mul_f32 v[32:33], v[32:33], v[84:85]
	s_nop 0
	v_pk_fma_f32 v[26:27], v[26:27], v[86:87], v[32:33]
	s_waitcnt vmcnt(14)
	v_pk_fma_f32 v[26:27], v[28:29], v[82:83], v[26:27]
	s_waitcnt lgkmcnt(0)
	v_mov_b32_e32 v29, v92
	s_waitcnt vmcnt(13)
	v_pk_fma_f32 v[26:27], v[30:31], v[96:97], v[26:27]
	v_mov_b32_e32 v92, v89
	s_waitcnt vmcnt(4)
	v_add_f32_e32 v26, v62, v26
	v_mov_b32_e32 v28, v88
	v_pk_mul_f32 v[30:31], v[40:41], v[92:93]
	v_add_f32_e32 v32, v26, v27
	v_mov_b32_e32 v26, v91
	v_mov_b32_e32 v91, v94
	v_pk_fma_f32 v[28:29], v[34:35], v[28:29], v[30:31]
	v_mov_b32_e32 v27, v95
	v_pk_fma_f32 v[28:29], v[36:37], v[90:91], v[28:29]
	s_nop 0
	v_pk_fma_f32 v[26:27], v[38:39], v[26:27], v[28:29]
	s_nop 0
	v_add_f32_e32 v26, v32, v26
	v_add_f32_e32 v26, v26, v27
	v_mul_f32_e64 v27, |v26|, s31
	v_exp_f32_e32 v27, v27
	v_min_f32_e32 v26, 0, v26
	v_add_f32_e32 v27, 1.0, v27
	v_cmp_gt_f32_e32 vcc, s28, v27
	s_nop 1
	v_cndmask_b32_e64 v28, 0, 32, vcc
	v_ldexp_f32 v27, v27, v28
	v_log_f32_e32 v27, v27
	s_nop 0
	v_mul_f32_e32 v28, 0x3f317217, v27
	v_fma_f32 v28, v27, s29, -v28
	v_fmac_f32_e32 v28, 0x3377d1cf, v27
	v_fmac_f32_e32 v28, 0x3f317217, v27
	v_cmp_lt_f32_e64 s[38:39], |v27|, s30
	s_nop 1
	v_cndmask_b32_e64 v27, v27, v28, s[38:39]
	v_cndmask_b32_e32 v28, 0, v180, vcc
	v_sub_f32_e32 v27, v27, v28
	v_sub_f32_e32 v26, v26, v27
	v_mul_f32_e32 v77, 0x3d800000, v26
.LBB0_451:
	s_or_b64 exec, exec, s[0:1]
	s_waitcnt vmcnt(11)
	v_add_f32_e32 v40, v25, v63
	s_waitcnt vmcnt(9)
	v_add_f32_e32 v38, v40, v66
	s_waitcnt vmcnt(5)
	v_add_f32_e32 v39, v38, v65
	v_add_f32_e32 v36, v39, v68
	v_add_f32_e32 v37, v36, v67
	v_add_f32_e32 v34, v37, v70
	v_add_f32_e32 v35, v34, v69
	v_add_f32_e32 v32, v35, v72
	v_add_f32_e32 v33, v32, v71
	v_add_f32_e32 v30, v33, v74
	v_add_f32_e32 v31, v30, v73
	v_add_f32_e32 v28, v31, v76
	v_add_f32_e32 v29, v28, v75
	v_add_f32_e32 v26, v29, v78
	v_add_f32_e32 v27, v26, v77
	v_lshl_add_u32 v23, v23, 2, 0
	ds_write_b32 v23, v27 offset:32768
	s_waitcnt vmcnt(4)
	v_lshl_add_u32 v62, v19, 2, 0
	v_cmp_lt_i32_e32 vcc, 0, v21
	v_mov_b32_e32 v23, 0
	v_mov_b32_e32 v41, 0
	s_waitcnt lgkmcnt(0)
	s_barrier
	s_and_saveexec_b64 s[0:1], vcc
	s_cbranch_execz .LBB0_453
	ds_read_b32 v41, v62 offset:32768
	s_waitcnt lgkmcnt(0)
	v_add_f32_e32 v41, 0, v41
